# v62 + P2 hgA chunk dS^T stores written through (sc1)
# baseline (speedup 1.0000x reference)
; #define LAS __attribute__((address_space(3)))
; __device__ __forceinline__ unsigned pk2(float lo, float hi) { f32x2_t v = {lo, hi}; bf16x2_t h = __builtin_convertvector(v, bf16x2_t); return __builtin_bit_cast(unsigned, h); }
; __device__ __forceinline__ void hgA_loop(Frame& F, int j0, int j1) {
;     ...
;         { const int kb = wave >> 1;
; #pragma unroll
;           for (int vbi = 0; vbi < 2; ++vbi) { const int vb = 2 * (wave & 1) + vbi; f32x16 acc = {};
; #pragma unroll
;               for (int ks = 0; ks < 4; ++ks) { const s16x8 a = *(const LAS s16x8*)(Kt + (32 * kb + r32) * HG_LDT + 16 * ks + 8 * hh); const s16x8 bb = *(const LAS s16x8*)(Vt + (32 * vb + r32) * HG_LDT + 16 * ks + 8 * hh);
;                   acc = __builtin_amdgcn_mfma_f32_32x32x16_bf16(a, bb, acc, 0, 0, 0); }
;               LAS bf16* dst = DSs + (32 * vb + r32) * HG_LDQ + 32 * kb + 4 * hh;
; #pragma unroll
;               for (int q = 0; q < 4; ++q) { v2u w; w.x = pk2(acc[4 * q], acc[4 * q + 1]); w.y = pk2(acc[4 * q + 2], acc[4 * q + 3]); *(LAS v2u*)(dst + 8 * q) = w; } } }
;         __syncthreads();
; #pragma unroll
;         for (int i = 0; i < 4; ++i) { const int p = tid + 512 * i; *(v4u*)(DSC + (size_t)p * 8) = *(const LAS v4u*)(DSs + (p >> 4) * HG_LDQ + (p & 15) * 8); }
;         { const int tb = wave >> 2, vb = wave & 3, t = 32 * tb + r32; f32x16 acc = {};
; #pragma unroll
;           for (int ks = 0; ks < 4; ++ks) if (ks < 2 * tb + 2) { const s16x8 a = *(const LAS s16x8*)(Vt + (32 * vb + r32) * HG_LDT + 16 * ks + 8 * hh); const s16x8 bb = *(const LAS s16x8*)(At + t * HG_LDT + 16 * ks + 8 * hh);
.LBB0_307:
	ds_read_b128 v[2:5], v53 offset:34816
	ds_read_b128 v[106:109], v53 offset:34848
	ds_read_b128 v[6:9], v80 offset:53248
	ds_read_b128 v[110:113], v80 offset:53280
	s_mov_b32 s44, 0x1b00000
	v_cndmask_b32_e64 v26, 0, 1, s[96:97]
	s_waitcnt lgkmcnt(1)
	v_mfma_f32_32x32x16_bf16 v[2:17], v[2:5], v[6:9], 0
	s_waitcnt lgkmcnt(0)
	v_mfma_f32_32x32x16_bf16 v[2:17], v[106:109], v[110:113], v[2:17]
	ds_read_b128 v[106:109], v53 offset:34880
	ds_read_b128 v[110:113], v80 offset:53312
	s_waitcnt lgkmcnt(0)
	v_mfma_f32_32x32x16_bf16 v[2:17], v[106:109], v[110:113], v[2:17]
	ds_read_b128 v[106:109], v53 offset:34912
	ds_read_b128 v[110:113], v80 offset:53344
	s_waitcnt lgkmcnt(0)
	v_mfma_f32_32x32x16_bf16 v[2:17], v[106:109], v[110:113], v[2:17]
	s_nop 11
	v_cvt_pk_bf16_f32 v2, v2, v3
	v_cvt_pk_bf16_f32 v3, v4, v5
	v_cvt_pk_bf16_f32 v4, v6, v7
	v_cvt_pk_bf16_f32 v5, v8, v9
	ds_write2_b64 v81, v[2:3], v[4:5] offset1:2
	v_cvt_pk_bf16_f32 v2, v10, v11
	v_cvt_pk_bf16_f32 v3, v12, v13
	v_cvt_pk_bf16_f32 v4, v14, v15
	v_cvt_pk_bf16_f32 v5, v16, v17
	ds_write2_b64 v81, v[2:3], v[4:5] offset0:4 offset1:6
	ds_read_b128 v[2:5], v53 offset:34816
	ds_read_b128 v[106:109], v53 offset:34848
	ds_read_b128 v[6:9], v80 offset:57856
	ds_read_b128 v[110:113], v80 offset:57888
	s_waitcnt lgkmcnt(1)
	v_mfma_f32_32x32x16_bf16 v[2:17], v[2:5], v[6:9], 0
	s_waitcnt lgkmcnt(0)
	v_mfma_f32_32x32x16_bf16 v[2:17], v[106:109], v[110:113], v[2:17]
	ds_read_b128 v[106:109], v53 offset:34880
	ds_read_b128 v[110:113], v80 offset:57920
	s_waitcnt lgkmcnt(0)
	v_mfma_f32_32x32x16_bf16 v[2:17], v[106:109], v[110:113], v[2:17]
	ds_read_b128 v[106:109], v53 offset:34912
	ds_read_b128 v[110:113], v80 offset:57952
	s_waitcnt lgkmcnt(0)
	v_mfma_f32_32x32x16_bf16 v[2:17], v[106:109], v[110:113], v[2:17]
	s_nop 11
	v_cvt_pk_bf16_f32 v2, v2, v3
	v_cvt_pk_bf16_f32 v3, v4, v5
	v_cvt_pk_bf16_f32 v4, v6, v7
	v_cvt_pk_bf16_f32 v5, v8, v9
	v_add_u32_e32 v6, 0x2000, v81
	ds_write2_b64 v6, v[2:3], v[4:5] offset0:64 offset1:66
	v_cvt_pk_bf16_f32 v2, v10, v11
	v_cvt_pk_bf16_f32 v3, v12, v13
	v_cvt_pk_bf16_f32 v4, v14, v15
	v_cvt_pk_bf16_f32 v5, v16, v17
	ds_write2_b64 v6, v[2:3], v[4:5] offset0:68 offset1:70
	s_waitcnt lgkmcnt(0)
	s_barrier
	ds_read_b128 v[2:5], v82
	v_lshl_add_u64 v[6:7], s[50:51], 0, v[36:37]
	v_add_co_u32_e32 v8, vcc, s44, v6
	s_mov_b32 s44, 0x1b02000
	s_nop 0
	v_addc_co_u32_e32 v9, vcc, 0, v7, vcc
	s_waitcnt lgkmcnt(0)
	global_store_dwordx4 v[8:9], v[2:5], off sc1
	ds_read_b128 v[2:5], v83
	v_add_co_u32_e32 v8, vcc, s44, v6
	s_mov_b32 s44, 0x1b04000
	s_nop 0
	v_addc_co_u32_e32 v9, vcc, 0, v7, vcc
	s_waitcnt lgkmcnt(0)
	global_store_dwordx4 v[8:9], v[2:5], off sc1
	ds_read_b128 v[2:5], v84
	v_add_co_u32_e32 v8, vcc, s44, v6
	v_cmp_ne_u32_e64 s[44:45], 1, v26
	s_nop 0
	v_addc_co_u32_e32 v9, vcc, 0, v7, vcc
	s_waitcnt lgkmcnt(0)
	global_store_dwordx4 v[8:9], v[2:5], off sc1
	ds_read_b128 v[2:5], v85
	v_add_co_u32_e32 v6, vcc, 0x1b06000, v6
	s_nop 1
	v_addc_co_u32_e32 v7, vcc, 0, v7, vcc
	s_waitcnt lgkmcnt(0)
	global_store_dwordx4 v[6:7], v[2:5], off sc1
	ds_read_b128 v[2:5], v54 offset:53248
	ds_read_b128 v[106:109], v54 offset:53280
	ds_read_b128 v[6:9], v55
	ds_read_b128 v[110:113], v55 offset:32
	s_waitcnt lgkmcnt(1)
	v_mfma_f32_32x32x16_bf16 v[2:17], v[2:5], v[6:9], 0
	s_andn2_b64 vcc, exec, s[96:97]
	s_waitcnt lgkmcnt(0)
	v_mfma_f32_32x32x16_bf16 v[2:17], v[106:109], v[110:113], v[2:17]
	s_cbranch_vccnz .LBB0_309
	ds_read_b128 v[106:109], v54 offset:53312
	ds_read_b128 v[110:113], v55 offset:64
	s_waitcnt lgkmcnt(0)
	v_mfma_f32_32x32x16_bf16 v[2:17], v[106:109], v[110:113], v[2:17]

; #define LAS __attribute__((address_space(3)))
; __device__ __forceinline__ unsigned pk2(float lo, float hi) { f32x2_t v = {lo, hi}; bf16x2_t h = __builtin_convertvector(v, bf16x2_t); return __builtin_bit_cast(unsigned, h); }
; __device__ __forceinline__ void hgA_loop(Frame& F, int j0, int j1) {
;     ...
;         { const int kb = wave >> 1;
; #pragma unroll
;           for (int vbi = 0; vbi < 2; ++vbi) { const int vb = 2 * (wave & 1) + vbi; f32x16 acc = {};
; #pragma unroll
;               for (int ks = 0; ks < 4; ++ks) { const s16x8 a = *(const LAS s16x8*)(Kt + (32 * kb + r32) * HG_LDT + 16 * ks + 8 * hh); const s16x8 bb = *(const LAS s16x8*)(Vt + (32 * vb + r32) * HG_LDT + 16 * ks + 8 * hh);
;                   acc = __builtin_amdgcn_mfma_f32_32x32x16_bf16(a, bb, acc, 0, 0, 0); }
;               LAS bf16* dst = DSs + (32 * vb + r32) * HG_LDQ + 32 * kb + 4 * hh;
; #pragma unroll
;               for (int q = 0; q < 4; ++q) { v2u w; w.x = pk2(acc[4 * q], acc[4 * q + 1]); w.y = pk2(acc[4 * q + 2], acc[4 * q + 3]); *(LAS v2u*)(dst + 8 * q) = w; } } }
;         __syncthreads();
; #pragma unroll
;         for (int i = 0; i < 4; ++i) { const int p = tid + 512 * i; *(v4u*)(DSC + (size_t)p * 8) = *(const LAS v4u*)(DSs + (p >> 4) * HG_LDQ + (p & 15) * 8); }
;         { const int tb = wave >> 2, vb = wave & 3, t = 32 * tb + r32; f32x16 acc = {};
; #pragma unroll
;           for (int ks = 0; ks < 4; ++ks) if (ks < 2 * tb + 2) { const s16x8 a = *(const LAS s16x8*)(Vt + (32 * vb + r32) * HG_LDT + 16 * ks + 8 * hh); const s16x8 bb = *(const LAS s16x8*)(At + t * HG_LDT + 16 * ks + 8 * hh);
.LBB0_385:
	ds_read_b128 v[2:5], v53 offset:34816
	ds_read_b128 v[106:109], v53 offset:34848
	ds_read_b128 v[6:9], v80 offset:53248
	ds_read_b128 v[110:113], v80 offset:53280
	s_mov_b32 s44, 0x1b00000
	v_cndmask_b32_e64 v39, 0, 1, s[92:93]
	s_waitcnt lgkmcnt(1)
	v_mfma_f32_32x32x16_bf16 v[2:17], v[2:5], v[6:9], 0
	s_waitcnt lgkmcnt(0)
	v_mfma_f32_32x32x16_bf16 v[2:17], v[106:109], v[110:113], v[2:17]
	ds_read_b128 v[106:109], v53 offset:34880
	ds_read_b128 v[110:113], v80 offset:53312
	s_waitcnt lgkmcnt(0)
	v_mfma_f32_32x32x16_bf16 v[2:17], v[106:109], v[110:113], v[2:17]
	ds_read_b128 v[106:109], v53 offset:34912
	ds_read_b128 v[110:113], v80 offset:53344
	s_waitcnt lgkmcnt(0)
	v_mfma_f32_32x32x16_bf16 v[2:17], v[106:109], v[110:113], v[2:17]
	s_nop 11
	v_cvt_pk_bf16_f32 v2, v2, v3
	v_cvt_pk_bf16_f32 v3, v4, v5
	v_cvt_pk_bf16_f32 v4, v6, v7
	v_cvt_pk_bf16_f32 v5, v8, v9
	ds_write2_b64 v81, v[2:3], v[4:5] offset1:2
	v_cvt_pk_bf16_f32 v2, v10, v11
	v_cvt_pk_bf16_f32 v3, v12, v13
	v_cvt_pk_bf16_f32 v4, v14, v15
	v_cvt_pk_bf16_f32 v5, v16, v17
	ds_write2_b64 v81, v[2:3], v[4:5] offset0:4 offset1:6
	ds_read_b128 v[2:5], v53 offset:34816
	ds_read_b128 v[106:109], v53 offset:34848
	ds_read_b128 v[6:9], v80 offset:57856
	ds_read_b128 v[110:113], v80 offset:57888
	s_waitcnt lgkmcnt(1)
	v_mfma_f32_32x32x16_bf16 v[2:17], v[2:5], v[6:9], 0
	s_waitcnt lgkmcnt(0)
	v_mfma_f32_32x32x16_bf16 v[2:17], v[106:109], v[110:113], v[2:17]
	ds_read_b128 v[106:109], v53 offset:34880
	ds_read_b128 v[110:113], v80 offset:57920
	s_waitcnt lgkmcnt(0)
	v_mfma_f32_32x32x16_bf16 v[2:17], v[106:109], v[110:113], v[2:17]
	ds_read_b128 v[106:109], v53 offset:34912
	ds_read_b128 v[110:113], v80 offset:57952
	s_waitcnt lgkmcnt(0)
	v_mfma_f32_32x32x16_bf16 v[2:17], v[106:109], v[110:113], v[2:17]
	s_nop 11
	v_cvt_pk_bf16_f32 v2, v2, v3
	v_cvt_pk_bf16_f32 v3, v4, v5
	v_cvt_pk_bf16_f32 v4, v6, v7
	v_cvt_pk_bf16_f32 v5, v8, v9
	v_add_u32_e32 v6, 0x2000, v81
	ds_write2_b64 v6, v[2:3], v[4:5] offset0:64 offset1:66
	v_cvt_pk_bf16_f32 v2, v10, v11
	v_cvt_pk_bf16_f32 v3, v12, v13
	v_cvt_pk_bf16_f32 v4, v14, v15
	v_cvt_pk_bf16_f32 v5, v16, v17
	ds_write2_b64 v6, v[2:3], v[4:5] offset0:68 offset1:70
	s_waitcnt lgkmcnt(0)
	s_barrier
	ds_read_b128 v[2:5], v82
	v_lshl_add_u64 v[6:7], s[50:51], 0, v[36:37]
	v_add_co_u32_e32 v8, vcc, s44, v6
	s_mov_b32 s44, 0x1b02000
	s_nop 0
	v_addc_co_u32_e32 v9, vcc, 0, v7, vcc
	s_waitcnt lgkmcnt(0)
	global_store_dwordx4 v[8:9], v[2:5], off sc1
	ds_read_b128 v[2:5], v83
	v_add_co_u32_e32 v8, vcc, s44, v6
	s_mov_b32 s44, 0x1b04000
	s_nop 0
	v_addc_co_u32_e32 v9, vcc, 0, v7, vcc
	s_waitcnt lgkmcnt(0)
	global_store_dwordx4 v[8:9], v[2:5], off sc1
	ds_read_b128 v[2:5], v84
	v_add_co_u32_e32 v8, vcc, s44, v6
	v_cmp_ne_u32_e64 s[44:45], 1, v39
	s_nop 0
	v_addc_co_u32_e32 v9, vcc, 0, v7, vcc
	s_waitcnt lgkmcnt(0)
	global_store_dwordx4 v[8:9], v[2:5], off sc1
	ds_read_b128 v[2:5], v85
	v_add_co_u32_e32 v6, vcc, 0x1b06000, v6
	s_nop 1
	v_addc_co_u32_e32 v7, vcc, 0, v7, vcc
	s_waitcnt lgkmcnt(0)
	global_store_dwordx4 v[6:7], v[2:5], off sc1
	ds_read_b128 v[2:5], v54 offset:53248
	ds_read_b128 v[106:109], v54 offset:53280
	ds_read_b128 v[6:9], v55
	ds_read_b128 v[110:113], v55 offset:32
	s_waitcnt lgkmcnt(1)
	v_mfma_f32_32x32x16_bf16 v[2:17], v[2:5], v[6:9], 0
	s_andn2_b64 vcc, exec, s[92:93]
	s_waitcnt lgkmcnt(0)
	v_mfma_f32_32x32x16_bf16 v[2:17], v[106:109], v[110:113], v[2:17]
	s_cbranch_vccnz .LBB0_387
	ds_read_b128 v[106:109], v54 offset:53312
	ds_read_b128 v[110:113], v55 offset:64
	s_waitcnt lgkmcnt(0)
	v_mfma_f32_32x32x16_bf16 v[2:17], v[106:109], v[110:113], v[2:17]

; #define LAS __attribute__((address_space(3)))
; __device__ __forceinline__ unsigned pk2(float lo, float hi) { f32x2_t v = {lo, hi}; bf16x2_t h = __builtin_convertvector(v, bf16x2_t); return __builtin_bit_cast(unsigned, h); }
; __device__ __forceinline__ void hgA_loop(Frame& F, int j0, int j1) {
;     ...
;         { const int kb = wave >> 1;
; #pragma unroll
;           for (int vbi = 0; vbi < 2; ++vbi) { const int vb = 2 * (wave & 1) + vbi; f32x16 acc = {};
; #pragma unroll
;               for (int ks = 0; ks < 4; ++ks) { const s16x8 a = *(const LAS s16x8*)(Kt + (32 * kb + r32) * HG_LDT + 16 * ks + 8 * hh); const s16x8 bb = *(const LAS s16x8*)(Vt + (32 * vb + r32) * HG_LDT + 16 * ks + 8 * hh);
;                   acc = __builtin_amdgcn_mfma_f32_32x32x16_bf16(a, bb, acc, 0, 0, 0); }
;               LAS bf16* dst = DSs + (32 * vb + r32) * HG_LDQ + 32 * kb + 4 * hh;
; #pragma unroll
;               for (int q = 0; q < 4; ++q) { v2u w; w.x = pk2(acc[4 * q], acc[4 * q + 1]); w.y = pk2(acc[4 * q + 2], acc[4 * q + 3]); *(LAS v2u*)(dst + 8 * q) = w; } } }
;         __syncthreads();
; #pragma unroll
;         for (int i = 0; i < 4; ++i) { const int p = tid + 512 * i; *(v4u*)(DSC + (size_t)p * 8) = *(const LAS v4u*)(DSs + (p >> 4) * HG_LDQ + (p & 15) * 8); }
;         { const int tb = wave >> 2, vb = wave & 3, t = 32 * tb + r32; f32x16 acc = {};
; #pragma unroll
;           for (int ks = 0; ks < 4; ++ks) if (ks < 2 * tb + 2) { const s16x8 a = *(const LAS s16x8*)(Vt + (32 * vb + r32) * HG_LDT + 16 * ks + 8 * hh); const s16x8 bb = *(const LAS s16x8*)(At + t * HG_LDT + 16 * ks + 8 * hh);
.LBB0_534:
	ds_read_b128 v[2:5], v54 offset:34816
	ds_read_b128 v[108:111], v54 offset:34848
	ds_read_b128 v[6:9], v82 offset:53248
	ds_read_b128 v[112:115], v82 offset:53280
	s_mov_b32 s44, 0x1b00000
	v_cndmask_b32_e64 v39, 0, 1, s[80:81]
	s_waitcnt lgkmcnt(1)
	v_mfma_f32_32x32x16_bf16 v[2:17], v[2:5], v[6:9], 0
	s_waitcnt lgkmcnt(0)
	v_mfma_f32_32x32x16_bf16 v[2:17], v[108:111], v[112:115], v[2:17]
	ds_read_b128 v[108:111], v54 offset:34880
	ds_read_b128 v[112:115], v82 offset:53312
	s_waitcnt lgkmcnt(0)
	v_mfma_f32_32x32x16_bf16 v[2:17], v[108:111], v[112:115], v[2:17]
	ds_read_b128 v[108:111], v54 offset:34912
	ds_read_b128 v[112:115], v82 offset:53344
	s_waitcnt lgkmcnt(0)
	v_mfma_f32_32x32x16_bf16 v[2:17], v[108:111], v[112:115], v[2:17]
	s_nop 11
	v_cvt_pk_bf16_f32 v2, v2, v3
	v_cvt_pk_bf16_f32 v3, v4, v5
	v_cvt_pk_bf16_f32 v4, v6, v7
	v_cvt_pk_bf16_f32 v5, v8, v9
	ds_write2_b64 v83, v[2:3], v[4:5] offset1:2
	v_cvt_pk_bf16_f32 v2, v10, v11
	v_cvt_pk_bf16_f32 v3, v12, v13
	v_cvt_pk_bf16_f32 v4, v14, v15
	v_cvt_pk_bf16_f32 v5, v16, v17
	ds_write2_b64 v83, v[2:3], v[4:5] offset0:4 offset1:6
	ds_read_b128 v[2:5], v54 offset:34816
	ds_read_b128 v[108:111], v54 offset:34848
	ds_read_b128 v[6:9], v82 offset:57856
	ds_read_b128 v[112:115], v82 offset:57888
	s_waitcnt lgkmcnt(1)
	v_mfma_f32_32x32x16_bf16 v[2:17], v[2:5], v[6:9], 0
	s_waitcnt lgkmcnt(0)
	v_mfma_f32_32x32x16_bf16 v[2:17], v[108:111], v[112:115], v[2:17]
	ds_read_b128 v[108:111], v54 offset:34880
	ds_read_b128 v[112:115], v82 offset:57920
	s_waitcnt lgkmcnt(0)
	v_mfma_f32_32x32x16_bf16 v[2:17], v[108:111], v[112:115], v[2:17]
	ds_read_b128 v[108:111], v54 offset:34912
	ds_read_b128 v[112:115], v82 offset:57952
	s_waitcnt lgkmcnt(0)
	v_mfma_f32_32x32x16_bf16 v[2:17], v[108:111], v[112:115], v[2:17]
	s_nop 11
	v_cvt_pk_bf16_f32 v2, v2, v3
	v_cvt_pk_bf16_f32 v3, v4, v5
	v_cvt_pk_bf16_f32 v4, v6, v7
	v_cvt_pk_bf16_f32 v5, v8, v9
	v_add_u32_e32 v6, 0x2000, v83
	ds_write2_b64 v6, v[2:3], v[4:5] offset0:64 offset1:66
	v_cvt_pk_bf16_f32 v2, v10, v11
	v_cvt_pk_bf16_f32 v3, v12, v13
	v_cvt_pk_bf16_f32 v4, v14, v15
	v_cvt_pk_bf16_f32 v5, v16, v17
	ds_write2_b64 v6, v[2:3], v[4:5] offset0:68 offset1:70
	s_waitcnt lgkmcnt(0)
	s_barrier
	ds_read_b128 v[2:5], v84
	v_lshl_add_u64 v[6:7], s[50:51], 0, v[36:37]
	v_add_co_u32_e32 v8, vcc, s44, v6
	s_mov_b32 s44, 0x1b02000
	s_nop 0
	v_addc_co_u32_e32 v9, vcc, 0, v7, vcc
	s_waitcnt lgkmcnt(0)
	global_store_dwordx4 v[8:9], v[2:5], off sc1
	ds_read_b128 v[2:5], v85
	v_add_co_u32_e32 v8, vcc, s44, v6
	s_mov_b32 s44, 0x1b04000
	s_nop 0
	v_addc_co_u32_e32 v9, vcc, 0, v7, vcc
	s_waitcnt lgkmcnt(0)
	global_store_dwordx4 v[8:9], v[2:5], off sc1
	ds_read_b128 v[2:5], v86
	v_add_co_u32_e32 v8, vcc, s44, v6
	v_cmp_ne_u32_e64 s[44:45], 1, v39
	s_nop 0
	v_addc_co_u32_e32 v9, vcc, 0, v7, vcc
	s_waitcnt lgkmcnt(0)
	global_store_dwordx4 v[8:9], v[2:5], off sc1
	ds_read_b128 v[2:5], v87
	v_add_co_u32_e32 v6, vcc, 0x1b06000, v6
	s_nop 1
	v_addc_co_u32_e32 v7, vcc, 0, v7, vcc
	s_waitcnt lgkmcnt(0)
	global_store_dwordx4 v[6:7], v[2:5], off sc1
	ds_read_b128 v[2:5], v55 offset:53248
	ds_read_b128 v[108:111], v55 offset:53280
	ds_read_b128 v[6:9], v56
	ds_read_b128 v[112:115], v56 offset:32
	s_waitcnt lgkmcnt(1)
	v_mfma_f32_32x32x16_bf16 v[2:17], v[2:5], v[6:9], 0
	s_andn2_b64 vcc, exec, s[80:81]
	s_waitcnt lgkmcnt(0)
	v_mfma_f32_32x32x16_bf16 v[2:17], v[108:111], v[112:115], v[2:17]
	s_cbranch_vccnz .LBB0_536
	ds_read_b128 v[108:111], v55 offset:53312
	ds_read_b128 v[112:115], v56 offset:64
	s_waitcnt lgkmcnt(0)
	v_mfma_f32_32x32x16_bf16 v[2:17], v[108:111], v[112:115], v[2:17]
